# adds: GLA-prep phase issues its 3 per-direction gate-input loads together; nt on the merge-1 epilogue gate loads
# baseline (speedup 1.0000x reference)
; __device__ __forceinline__ void phase_g0(const Args& a, unsigned char* smem, int tid, int lane, int wave, bf16_t* QEFdst) {
;     ...
;             { const int idx = tid * 2, t = idx >> 4, r = idx & 15; *(f32x2*)(lr + idx) = *(const f32x2*)(BG + (size_t)(row0 + t) * 32 + dir * 16 + r); }
;             { const int idx = tid * 4, r = idx >> 7, p = idx & 127; *(f32x4*)(w2s + idx) = *(const f32x4*)(a.w_gate2 + (size_t)(dir * 16 + r) * 512 + h * 128 + p); }
;             if (tid < 128) bs[tid] = a.b_gate[dir * 512 + h * 128 + tid];
.LBB0_523:
	s_lshl_b32 s78, s1, 4
	s_and_saveexec_b64 s[54:55], s[6:7]
	v_lshl_or_b32 v24, s1, 9, v217
	v_lshl_add_u64 v[126:127], v[24:25], 2, s[62:63]
	global_load_dword v253, v[126:127], off
	s_or_b64 exec, exec, s[54:55]
	v_lshl_add_u64 v[126:127], s[78:79], 2, v[100:101]
	global_load_dwordx2 v[254:255], v[126:127], off
	v_add_lshl_u32 v24, s78, v41, 9
	v_lshl_add_u64 v[126:127], v[24:25], 2, v[118:119]
	global_load_dwordx4 v[126:129], v[126:127], off
	s_waitcnt vmcnt(0)
	ds_write_b64 v33, v[254:255]
	ds_write_b128 v142, v[126:129] offset:4096
	s_and_saveexec_b64 s[54:55], s[6:7]
	ds_write_b32 v211, v253 offset:12288

; __device__ __forceinline__ unsigned pk2(float lo, float hi) { const f32x2 v = {lo, hi}; const bf16x2_t b = __builtin_convertvector(v, bf16x2_t); return __builtin_bit_cast(unsigned, b); }
; __device__ __forceinline__ float sigmoid_f(float v) { return __builtin_amdgcn_rcpf(1.f + __expf(-v)); }
;     __device__ __forceinline__ void operator()(const f32x4 (&acc)[2][2][4][2], const pg8::Unit& u, int wr, int wc, int fr, int fq) const {
;         const int row0 = u.pm * 256 + wr * 64 + fr, col0 = u.pn * 256 + wc * 32 + 8 * fq;
; #pragma unroll
;         for (int ai = 0; ai < 2; ++ai) {
;             u32x4 gb[4][2];
; #pragma unroll
;             for (int m = 0; m < 4; ++m)
; #pragma unroll
;                 for (int bj = 0; bj < 2; ++bj) gb[m][bj] = *(const u32x4*)(G + (size_t)(row0 + ai * 128 + m * 16) * 2048 + col0 + bj * 128);
;             asm volatile("" ::: "memory");
; #pragma unroll
;             for (int m = 0; m < 4; ++m) { bf16_t* rowp = G + (size_t)(row0 + ai * 128 + m * 16) * 2048 + col0;
; #pragma unroll
;                 for (int bj = 0; bj < 2; ++bj) { const u32x4 g = gb[m][bj]; const f32x4 v0 = acc[ai][bj][m][0], v1 = acc[ai][bj][m][1];
;                     u32x4 w; w.x = pk2(sigmoid_f(bflo(g.x)) * v0[0], sigmoid_f(bfhi(g.x)) * v0[1]); w.y = pk2(sigmoid_f(bflo(g.y)) * v0[2], sigmoid_f(bfhi(g.y)) * v0[3]);
;                     w.z = pk2(sigmoid_f(bflo(g.z)) * v1[0], sigmoid_f(bfhi(g.z)) * v1[1]); w.w = pk2(sigmoid_f(bflo(g.w)) * v1[2], sigmoid_f(bfhi(g.w)) * v1[3]);
;                     *(u32x4*)(rowp + bj * 128) = w; } }
.LBB0_843:
	v_lshl_or_b32 v130, s1, 8, v195
	v_lshl_add_u32 v128, s36, 8, v193
	v_ashrrev_i32_e32 v131, 31, v130
	v_lshlrev_b64 v[170:171], 1, v[130:131]
	v_ashrrev_i32_e32 v129, 31, v128
	v_lshl_add_u64 v[172:173], s[8:9], 0, v[170:171]
	v_lshlrev_b64 v[174:175], 12, v[128:129]
	v_lshl_add_u64 v[130:131], v[172:173], 0, v[174:175]
	global_load_dwordx4 v[200:203], v[130:131], off nt
	global_load_dwordx4 v[204:207], v[130:131], off offset:256 nt
	v_or_b32_e32 v130, 16, v128
	v_or_b32_e32 v132, 32, v128
	v_or_b32_e32 v128, 48, v128
	v_ashrrev_i32_e32 v131, 31, v130
	v_ashrrev_i32_e32 v133, 31, v132
	v_ashrrev_i32_e32 v129, 31, v128
	v_lshlrev_b64 v[208:209], 12, v[130:131]
	v_lshlrev_b64 v[178:179], 12, v[132:133]
	v_lshlrev_b64 v[176:177], 12, v[128:129]
	v_lshl_add_u64 v[128:129], s[8:9], 0, v[174:175]
	v_lshl_add_u64 v[130:131], v[172:173], 0, v[208:209]
	v_lshl_add_u64 v[132:133], v[172:173], 0, v[178:179]
	v_lshl_add_u64 v[210:211], v[172:173], 0, v[176:177]
	v_lshl_add_u64 v[212:213], v[128:129], 0, v[170:171]
	global_load_dwordx4 v[148:151], v[130:131], off nt
	global_load_dwordx4 v[144:147], v[130:131], off offset:256 nt
	global_load_dwordx4 v[140:143], v[132:133], off nt
	global_load_dwordx4 v[136:139], v[132:133], off offset:256 nt
	s_nop 0
	global_load_dwordx4 v[132:135], v[210:211], off nt
	global_load_dwordx4 v[128:131], v[210:211], off offset:256 nt
	s_andn2_b64 vcc, exec, s[4:5]
	s_mov_b64 s[4:5], -1
	s_waitcnt vmcnt(0)
	v_lshlrev_b32_e32 v199, 16, v200
	v_and_b32_e32 v200, 0xffff0000, v200
	v_lshlrev_b32_e32 v210, 16, v201
	v_and_b32_e32 v201, 0xffff0000, v201
	v_lshlrev_b32_e32 v211, 16, v202
	v_and_b32_e32 v202, 0xffff0000, v202
	v_lshlrev_b32_e32 v214, 16, v203
	v_and_b32_e32 v203, 0xffff0000, v203
	v_lshlrev_b32_e32 v215, 16, v204
	v_and_b32_e32 v204, 0xffff0000, v204
	v_mul_f32_e32 v199, 0xbfb8aa3b, v199
	v_mul_f32_e32 v200, 0xbfb8aa3b, v200
	v_mul_f32_e32 v210, 0xbfb8aa3b, v210
	v_mul_f32_e32 v201, 0xbfb8aa3b, v201
	v_mul_f32_e32 v211, 0xbfb8aa3b, v211
	v_mul_f32_e32 v202, 0xbfb8aa3b, v202
	v_mul_f32_e32 v214, 0xbfb8aa3b, v214
	v_mul_f32_e32 v203, 0xbfb8aa3b, v203
	v_mul_f32_e32 v215, 0xbfb8aa3b, v215
	v_mul_f32_e32 v204, 0xbfb8aa3b, v204
	v_exp_f32_e32 v199, v199
	v_exp_f32_e32 v200, v200
	v_exp_f32_e32 v210, v210
	v_exp_f32_e32 v201, v201
	v_exp_f32_e32 v211, v211
	v_exp_f32_e32 v202, v202
	v_exp_f32_e32 v214, v214
	v_exp_f32_e32 v203, v203
	v_exp_f32_e32 v215, v215
	v_exp_f32_e32 v204, v204
	v_lshlrev_b32_e32 v216, 16, v205
	v_and_b32_e32 v205, 0xffff0000, v205
	v_mul_f32_e32 v205, 0xbfb8aa3b, v205
	v_exp_f32_e32 v217, v205
	v_add_f32_e32 v199, 1.0, v199
	v_add_f32_e32 v205, 1.0, v200
	v_add_f32_e32 v210, 1.0, v210
	v_add_f32_e32 v218, 1.0, v201
	v_add_f32_e32 v211, 1.0, v211
	v_add_f32_e32 v219, 1.0, v202
	v_add_f32_e32 v214, 1.0, v214
	v_add_f32_e32 v220, 1.0, v203
	v_add_f32_e32 v215, 1.0, v215
	v_add_f32_e32 v221, 1.0, v204
	v_rcp_f32_e32 v200, v199
	v_rcp_f32_e32 v201, v205
	v_rcp_f32_e32 v202, v210
	v_rcp_f32_e32 v203, v218
	v_rcp_f32_e32 v204, v211
	v_rcp_f32_e32 v205, v219
	v_rcp_f32_e32 v210, v214
	v_rcp_f32_e32 v211, v220
	v_rcp_f32_e32 v214, v215
	v_rcp_f32_e32 v215, v221
	v_mul_f32_e32 v216, 0xbfb8aa3b, v216
	v_exp_f32_e32 v216, v216
	v_pk_mul_f32 v[124:125], v[124:125], v[200:201]
	v_pk_mul_f32 v[126:127], v[126:127], v[202:203]
	v_pk_mul_f32 v[200:201], v[120:121], v[204:205]
	v_pk_mul_f32 v[202:203], v[122:123], v[210:211]
	v_pk_mul_f32 v[116:117], v[116:117], v[214:215]
	v_cvt_pk_bf16_f32 v120, v124, v125
	v_cvt_pk_bf16_f32 v121, v126, v127
	v_cvt_pk_bf16_f32 v122, v200, v201
	v_cvt_pk_bf16_f32 v123, v202, v203
	v_cvt_pk_bf16_f32 v116, v116, v117
	v_add_f32_e32 v117, 1.0, v217
	v_add_f32_e32 v216, 1.0, v216
	global_store_dwordx4 v[212:213], v[120:123], off
	s_nop 1
	v_rcp_f32_e32 v121, v117
	v_lshlrev_b32_e32 v117, 16, v206
	v_rcp_f32_e32 v120, v216
	v_mul_f32_e32 v117, 0xbfb8aa3b, v117
	v_and_b32_e32 v122, 0xffff0000, v206
	v_exp_f32_e32 v117, v117
	v_mul_f32_e32 v122, 0xbfb8aa3b, v122
	v_exp_f32_e32 v122, v122
	v_pk_mul_f32 v[118:119], v[118:119], v[120:121]
	v_lshlrev_b32_e32 v121, 16, v207
	v_add_f32_e32 v117, 1.0, v117
	v_mul_f32_e32 v121, 0xbfb8aa3b, v121
	v_rcp_f32_e32 v120, v117
	v_add_f32_e32 v117, 1.0, v122
	v_exp_f32_e32 v122, v121
	v_and_b32_e32 v121, 0xffff0000, v207
	v_mul_f32_e32 v121, 0xbfb8aa3b, v121
	v_exp_f32_e32 v123, v121
	v_rcp_f32_e32 v121, v117
	v_add_f32_e32 v117, 1.0, v122
	v_rcp_f32_e32 v122, v117
	v_add_f32_e32 v117, 1.0, v123
	v_rcp_f32_e32 v123, v117
	v_pk_mul_f32 v[112:113], v[112:113], v[120:121]
	v_cvt_pk_bf16_f32 v117, v118, v119
	v_cvt_pk_bf16_f32 v118, v112, v113
	v_pk_mul_f32 v[112:113], v[114:115], v[122:123]
	v_lshlrev_b32_e32 v114, 16, v148
	v_and_b32_e32 v115, 0xffff0000, v148
	v_mul_f32_e32 v114, 0xbfb8aa3b, v114
	v_mul_f32_e32 v115, 0xbfb8aa3b, v115
	v_exp_f32_e32 v114, v114
	v_exp_f32_e32 v115, v115
	v_cvt_pk_bf16_f32 v119, v112, v113
	global_store_dwordx4 v[212:213], v[116:119], off offset:256
	v_add_f32_e32 v114, 1.0, v114
	v_add_f32_e32 v115, 1.0, v115
	v_lshlrev_b32_e32 v116, 16, v149
	v_and_b32_e32 v117, 0xffff0000, v149
	v_mul_f32_e32 v116, 0xbfb8aa3b, v116
	v_mul_f32_e32 v117, 0xbfb8aa3b, v117
	v_rcp_f32_e32 v114, v114
	v_rcp_f32_e32 v115, v115
	v_exp_f32_e32 v116, v116
	v_exp_f32_e32 v117, v117
	v_lshl_add_u64 v[112:113], s[8:9], 0, v[208:209]
	v_pk_mul_f32 v[108:109], v[108:109], v[114:115]
	v_add_f32_e32 v114, 1.0, v116
	v_add_f32_e32 v115, 1.0, v117
	v_rcp_f32_e32 v114, v114
	v_lshlrev_b32_e32 v116, 16, v150
	v_and_b32_e32 v117, 0xffff0000, v150
	v_rcp_f32_e32 v115, v115
	v_mul_f32_e32 v116, 0xbfb8aa3b, v116
	v_mul_f32_e32 v117, 0xbfb8aa3b, v117
; __device__ __forceinline__ unsigned pk2(float lo, float hi) { const f32x2 v = {lo, hi}; const bf16x2_t b = __builtin_convertvector(v, bf16x2_t); return __builtin_bit_cast(unsigned, b); }
; __device__ __forceinline__ float sigmoid_f(float v) { return __builtin_amdgcn_rcpf(1.f + __expf(-v)); }
;     __device__ __forceinline__ void operator()(const f32x4 (&acc)[2][2][4][2], const pg8::Unit& u, int wr, int wc, int fr, int fq) const {
;     ...
;             for (int m = 0; m < 4; ++m) { bf16_t* rowp = G + (size_t)(row0 + ai * 128 + m * 16) * 2048 + col0;
; #pragma unroll
;                 for (int bj = 0; bj < 2; ++bj) { const u32x4 g = gb[m][bj]; const f32x4 v0 = acc[ai][bj][m][0], v1 = acc[ai][bj][m][1];
;                     u32x4 w; w.x = pk2(sigmoid_f(bflo(g.x)) * v0[0], sigmoid_f(bfhi(g.x)) * v0[1]); w.y = pk2(sigmoid_f(bflo(g.y)) * v0[2], sigmoid_f(bfhi(g.y)) * v0[3]);
;                     w.z = pk2(sigmoid_f(bflo(g.z)) * v1[0], sigmoid_f(bfhi(g.z)) * v1[1]); w.w = pk2(sigmoid_f(bflo(g.w)) * v1[2], sigmoid_f(bfhi(g.w)) * v1[3]);
;                     *(u32x4*)(rowp + bj * 128) = w; } }
	v_exp_f32_e32 v116, v116
	v_exp_f32_e32 v117, v117
	v_pk_mul_f32 v[110:111], v[110:111], v[114:115]
	v_cvt_pk_bf16_f32 v108, v108, v109
	v_cvt_pk_bf16_f32 v109, v110, v111
	v_lshlrev_b32_e32 v110, 16, v151
	v_add_f32_e32 v116, 1.0, v116
	v_add_f32_e32 v117, 1.0, v117
	v_mul_f32_e32 v110, 0xbfb8aa3b, v110
	v_rcp_f32_e32 v116, v116
	v_rcp_f32_e32 v117, v117
	v_exp_f32_e32 v111, v110
	v_and_b32_e32 v110, 0xffff0000, v151
	v_mul_f32_e32 v110, 0xbfb8aa3b, v110
	v_exp_f32_e32 v114, v110
	v_pk_mul_f32 v[104:105], v[104:105], v[116:117]
	v_lshl_add_u64 v[112:113], v[112:113], 0, v[170:171]
	v_cvt_pk_bf16_f32 v110, v104, v105
	v_add_f32_e32 v104, 1.0, v111
	v_lshlrev_b32_e32 v111, 16, v144
	v_add_f32_e32 v105, 1.0, v114
	v_mul_f32_e32 v111, 0xbfb8aa3b, v111
	v_and_b32_e32 v114, 0xffff0000, v144
	v_exp_f32_e32 v111, v111
	v_mul_f32_e32 v114, 0xbfb8aa3b, v114
	v_rcp_f32_e32 v104, v104
	v_exp_f32_e32 v115, v114
	v_rcp_f32_e32 v105, v105
	v_add_f32_e32 v111, 1.0, v111
	v_rcp_f32_e32 v114, v111
	v_add_f32_e32 v111, 1.0, v115
	v_pk_mul_f32 v[104:105], v[106:107], v[104:105]
	v_rcp_f32_e32 v115, v111
	v_cvt_pk_bf16_f32 v111, v104, v105
	v_lshlrev_b32_e32 v104, 16, v145
	v_mul_f32_e32 v104, 0xbfb8aa3b, v104
	v_and_b32_e32 v105, 0xffff0000, v145
	v_exp_f32_e32 v104, v104
	v_mul_f32_e32 v105, 0xbfb8aa3b, v105
	v_exp_f32_e32 v105, v105
	v_pk_mul_f32 v[100:101], v[100:101], v[114:115]
	v_and_b32_e32 v106, 0xffff0000, v146
	v_cvt_pk_bf16_f32 v100, v100, v101
	v_add_f32_e32 v101, 1.0, v104
	v_rcp_f32_e32 v104, v101
	v_add_f32_e32 v101, 1.0, v105
	v_rcp_f32_e32 v105, v101
	v_lshlrev_b32_e32 v101, 16, v146
	v_mul_f32_e32 v101, 0xbfb8aa3b, v101
	v_exp_f32_e32 v101, v101
	v_mul_f32_e32 v106, 0xbfb8aa3b, v106
	v_exp_f32_e32 v106, v106
	v_pk_mul_f32 v[102:103], v[102:103], v[104:105]
	v_lshlrev_b32_e32 v105, 16, v147
	v_add_f32_e32 v101, 1.0, v101
	v_mul_f32_e32 v105, 0xbfb8aa3b, v105
	v_rcp_f32_e32 v104, v101
	v_add_f32_e32 v101, 1.0, v106
	v_exp_f32_e32 v106, v105
	v_and_b32_e32 v105, 0xffff0000, v147
	v_mul_f32_e32 v105, 0xbfb8aa3b, v105
	v_exp_f32_e32 v107, v105
	v_rcp_f32_e32 v105, v101
	v_add_f32_e32 v101, 1.0, v106
	v_rcp_f32_e32 v106, v101
	v_add_f32_e32 v101, 1.0, v107
	v_rcp_f32_e32 v107, v101
	v_pk_mul_f32 v[96:97], v[96:97], v[104:105]
	v_cvt_pk_bf16_f32 v101, v102, v103
	v_cvt_pk_bf16_f32 v102, v96, v97
	v_pk_mul_f32 v[96:97], v[98:99], v[106:107]
	v_lshlrev_b32_e32 v98, 16, v140
	v_and_b32_e32 v99, 0xffff0000, v140
	v_mul_f32_e32 v98, 0xbfb8aa3b, v98
	v_mul_f32_e32 v99, 0xbfb8aa3b, v99
	v_exp_f32_e32 v98, v98
	v_exp_f32_e32 v99, v99
	v_cvt_pk_bf16_f32 v103, v96, v97
	global_store_dwordx4 v[112:113], v[100:103], off offset:256
	v_add_f32_e32 v98, 1.0, v98
	v_add_f32_e32 v99, 1.0, v99
	v_lshlrev_b32_e32 v100, 16, v141
	v_and_b32_e32 v101, 0xffff0000, v141
	v_mul_f32_e32 v100, 0xbfb8aa3b, v100
	v_mul_f32_e32 v101, 0xbfb8aa3b, v101
	v_rcp_f32_e32 v98, v98
	v_rcp_f32_e32 v99, v99
	v_exp_f32_e32 v100, v100
	v_exp_f32_e32 v101, v101
	v_lshl_add_u64 v[96:97], s[8:9], 0, v[178:179]
	v_pk_mul_f32 v[92:93], v[92:93], v[98:99]
	v_add_f32_e32 v98, 1.0, v100
	v_add_f32_e32 v99, 1.0, v101
	v_rcp_f32_e32 v98, v98
	v_lshlrev_b32_e32 v100, 16, v142
	v_and_b32_e32 v101, 0xffff0000, v142
	v_rcp_f32_e32 v99, v99
	v_mul_f32_e32 v100, 0xbfb8aa3b, v100
	v_mul_f32_e32 v101, 0xbfb8aa3b, v101
	v_exp_f32_e32 v100, v100
	v_exp_f32_e32 v101, v101
	v_pk_mul_f32 v[94:95], v[94:95], v[98:99]
	v_cvt_pk_bf16_f32 v92, v92, v93
	v_cvt_pk_bf16_f32 v93, v94, v95
	v_lshlrev_b32_e32 v94, 16, v143
	v_add_f32_e32 v100, 1.0, v100
	v_add_f32_e32 v101, 1.0, v101
	v_mul_f32_e32 v94, 0xbfb8aa3b, v94
	v_rcp_f32_e32 v100, v100
	v_rcp_f32_e32 v101, v101
	v_exp_f32_e32 v95, v94
	v_and_b32_e32 v94, 0xffff0000, v143
	v_mul_f32_e32 v94, 0xbfb8aa3b, v94
	v_exp_f32_e32 v98, v94
	v_pk_mul_f32 v[88:89], v[88:89], v[100:101]
	v_lshl_add_u64 v[96:97], v[96:97], 0, v[170:171]
	v_cvt_pk_bf16_f32 v94, v88, v89
	v_add_f32_e32 v88, 1.0, v95
	v_lshlrev_b32_e32 v95, 16, v136
	v_add_f32_e32 v89, 1.0, v98
	v_mul_f32_e32 v95, 0xbfb8aa3b, v95
	v_and_b32_e32 v98, 0xffff0000, v136
	v_exp_f32_e32 v95, v95
	v_mul_f32_e32 v98, 0xbfb8aa3b, v98
	v_rcp_f32_e32 v88, v88
	v_exp_f32_e32 v99, v98
	v_rcp_f32_e32 v89, v89
	v_add_f32_e32 v95, 1.0, v95
	v_rcp_f32_e32 v98, v95
	v_add_f32_e32 v95, 1.0, v99
	v_pk_mul_f32 v[88:89], v[90:91], v[88:89]
	v_rcp_f32_e32 v99, v95
	v_cvt_pk_bf16_f32 v95, v88, v89
	v_lshlrev_b32_e32 v88, 16, v137
	v_mul_f32_e32 v88, 0xbfb8aa3b, v88
	v_and_b32_e32 v89, 0xffff0000, v137
	v_exp_f32_e32 v88, v88
	v_mul_f32_e32 v89, 0xbfb8aa3b, v89
	v_exp_f32_e32 v89, v89
	v_pk_mul_f32 v[84:85], v[84:85], v[98:99]
	v_and_b32_e32 v90, 0xffff0000, v138
	v_cvt_pk_bf16_f32 v84, v84, v85
	v_add_f32_e32 v85, 1.0, v88
	v_rcp_f32_e32 v88, v85
	v_add_f32_e32 v85, 1.0, v89
	v_rcp_f32_e32 v89, v85
	v_lshlrev_b32_e32 v85, 16, v138
	v_mul_f32_e32 v85, 0xbfb8aa3b, v85
	v_exp_f32_e32 v85, v85
	v_mul_f32_e32 v90, 0xbfb8aa3b, v90
	v_exp_f32_e32 v90, v90
	v_pk_mul_f32 v[86:87], v[86:87], v[88:89]
	v_lshlrev_b32_e32 v89, 16, v139
	v_add_f32_e32 v85, 1.0, v85
	v_mul_f32_e32 v89, 0xbfb8aa3b, v89
	v_rcp_f32_e32 v88, v85
	v_add_f32_e32 v85, 1.0, v90
	v_exp_f32_e32 v90, v89
	v_and_b32_e32 v89, 0xffff0000, v139
	v_mul_f32_e32 v89, 0xbfb8aa3b, v89
	v_exp_f32_e32 v91, v89
	v_rcp_f32_e32 v89, v85
	v_add_f32_e32 v85, 1.0, v90
	v_rcp_f32_e32 v90, v85
	v_add_f32_e32 v85, 1.0, v91
	v_rcp_f32_e32 v91, v85
	v_pk_mul_f32 v[80:81], v[80:81], v[88:89]
	v_cvt_pk_bf16_f32 v85, v86, v87
	v_cvt_pk_bf16_f32 v86, v80, v81
	v_pk_mul_f32 v[80:81], v[82:83], v[90:91]
	v_lshlrev_b32_e32 v82, 16, v132
	v_and_b32_e32 v83, 0xffff0000, v132
	v_mul_f32_e32 v82, 0xbfb8aa3b, v82
; __device__ __forceinline__ unsigned pk2(float lo, float hi) { const f32x2 v = {lo, hi}; const bf16x2_t b = __builtin_convertvector(v, bf16x2_t); return __builtin_bit_cast(unsigned, b); }
; __device__ __forceinline__ float sigmoid_f(float v) { return __builtin_amdgcn_rcpf(1.f + __expf(-v)); }
;     __device__ __forceinline__ void operator()(const f32x4 (&acc)[2][2][4][2], const pg8::Unit& u, int wr, int wc, int fr, int fq) const {
;     ...
;         for (int ai = 0; ai < 2; ++ai) {
;             u32x4 gb[4][2];
; #pragma unroll
;             for (int m = 0; m < 4; ++m)
; #pragma unroll
;                 for (int bj = 0; bj < 2; ++bj) gb[m][bj] = *(const u32x4*)(G + (size_t)(row0 + ai * 128 + m * 16) * 2048 + col0 + bj * 128);
;             asm volatile("" ::: "memory");
; #pragma unroll
;             for (int m = 0; m < 4; ++m) { bf16_t* rowp = G + (size_t)(row0 + ai * 128 + m * 16) * 2048 + col0;
; #pragma unroll
;                 for (int bj = 0; bj < 2; ++bj) { const u32x4 g = gb[m][bj]; const f32x4 v0 = acc[ai][bj][m][0], v1 = acc[ai][bj][m][1];
;                     u32x4 w; w.x = pk2(sigmoid_f(bflo(g.x)) * v0[0], sigmoid_f(bfhi(g.x)) * v0[1]); w.y = pk2(sigmoid_f(bflo(g.y)) * v0[2], sigmoid_f(bfhi(g.y)) * v0[3]);
;                     w.z = pk2(sigmoid_f(bflo(g.z)) * v1[0], sigmoid_f(bfhi(g.z)) * v1[1]); w.w = pk2(sigmoid_f(bflo(g.w)) * v1[2], sigmoid_f(bfhi(g.w)) * v1[3]);
;                     *(u32x4*)(rowp + bj * 128) = w; } }
	v_mul_f32_e32 v83, 0xbfb8aa3b, v83
	v_exp_f32_e32 v82, v82
	v_exp_f32_e32 v83, v83
	v_cvt_pk_bf16_f32 v87, v80, v81
	global_store_dwordx4 v[96:97], v[84:87], off offset:256
	v_add_f32_e32 v80, 1.0, v82
	v_add_f32_e32 v81, 1.0, v83
	v_rcp_f32_e32 v80, v80
	v_rcp_f32_e32 v81, v81
	v_and_b32_e32 v84, 0xffff0000, v134
	v_mul_f32_e32 v84, 0xbfb8aa3b, v84
	v_exp_f32_e32 v84, v84
	v_pk_mul_f32 v[76:77], v[76:77], v[80:81]
	v_lshlrev_b32_e32 v80, 16, v133
	v_mul_f32_e32 v80, 0xbfb8aa3b, v80
	v_and_b32_e32 v81, 0xffff0000, v133
	v_exp_f32_e32 v80, v80
	v_mul_f32_e32 v81, 0xbfb8aa3b, v81
	v_exp_f32_e32 v81, v81
	v_cvt_pk_bf16_f32 v76, v76, v77
	v_add_f32_e32 v77, 1.0, v80
	v_rcp_f32_e32 v80, v77
	v_add_f32_e32 v77, 1.0, v81
	v_rcp_f32_e32 v81, v77
	v_lshlrev_b32_e32 v77, 16, v134
	v_mul_f32_e32 v77, 0xbfb8aa3b, v77
	v_exp_f32_e32 v77, v77
	v_lshl_add_u64 v[100:101], v[174:175], 0, s[18:19]
	v_pk_mul_f32 v[78:79], v[78:79], v[80:81]
	v_lshlrev_b32_e32 v81, 16, v135
	v_add_f32_e32 v77, 1.0, v77
	v_rcp_f32_e32 v80, v77
	v_add_f32_e32 v77, 1.0, v84
	v_lshl_add_u64 v[84:85], v[172:173], 0, v[100:101]
	global_load_dwordx4 v[88:91], v[84:85], off nt
	v_mul_f32_e32 v81, 0xbfb8aa3b, v81
	v_exp_f32_e32 v86, v81
	v_and_b32_e32 v81, 0xffff0000, v135
	v_mul_f32_e32 v81, 0xbfb8aa3b, v81
	v_exp_f32_e32 v87, v81
	v_rcp_f32_e32 v81, v77
	v_add_f32_e32 v77, 1.0, v86
	v_rcp_f32_e32 v86, v77
	v_add_f32_e32 v77, 1.0, v87
	v_rcp_f32_e32 v87, v77
	v_pk_mul_f32 v[72:73], v[72:73], v[80:81]
	global_store_dwordx4 v[96:97], v[92:95], off
	v_cvt_pk_bf16_f32 v77, v78, v79
	v_cvt_pk_bf16_f32 v78, v72, v73
	v_pk_mul_f32 v[72:73], v[74:75], v[86:87]
	v_lshlrev_b32_e32 v74, 16, v128
	v_and_b32_e32 v75, 0xffff0000, v128
	global_load_dwordx4 v[92:95], v[84:85], off offset:256 nt
	v_mul_f32_e32 v74, 0xbfb8aa3b, v74
	v_mul_f32_e32 v75, 0xbfb8aa3b, v75
	v_exp_f32_e32 v74, v74
	v_exp_f32_e32 v75, v75
	v_cvt_pk_bf16_f32 v79, v72, v73
	v_lshl_add_u64 v[82:83], s[8:9], 0, v[176:177]
	v_add_f32_e32 v72, 1.0, v74
	v_add_f32_e32 v73, 1.0, v75
	v_rcp_f32_e32 v72, v72
	v_rcp_f32_e32 v73, v73
	v_lshlrev_b32_e32 v74, 16, v129
	v_and_b32_e32 v75, 0xffff0000, v129
	v_mul_f32_e32 v74, 0xbfb8aa3b, v74
	v_mul_f32_e32 v75, 0xbfb8aa3b, v75
	v_pk_mul_f32 v[68:69], v[68:69], v[72:73]
	v_exp_f32_e32 v74, v74
	v_exp_f32_e32 v75, v75
	v_cvt_pk_bf16_f32 v68, v68, v69
	v_lshlrev_b32_e32 v69, 16, v130
	v_mul_f32_e32 v69, 0xbfb8aa3b, v69
	v_and_b32_e32 v72, 0xffff0000, v130
	v_exp_f32_e32 v69, v69
	v_mul_f32_e32 v72, 0xbfb8aa3b, v72
	v_exp_f32_e32 v73, v72
	v_add_f32_e32 v74, 1.0, v74
	v_add_f32_e32 v75, 1.0, v75
	v_rcp_f32_e32 v74, v74
	v_rcp_f32_e32 v75, v75
	v_add_f32_e32 v69, 1.0, v69
	v_rcp_f32_e32 v72, v69
	v_add_f32_e32 v69, 1.0, v73
	v_lshlrev_b32_e32 v73, 16, v131
	v_mul_f32_e32 v73, 0xbfb8aa3b, v73
	v_pk_mul_f32 v[70:71], v[70:71], v[74:75]
	v_exp_f32_e32 v74, v73
	v_and_b32_e32 v73, 0xffff0000, v131
	v_mul_f32_e32 v73, 0xbfb8aa3b, v73
	v_exp_f32_e32 v75, v73
	v_rcp_f32_e32 v73, v69
	v_add_f32_e32 v69, 1.0, v74
	v_rcp_f32_e32 v74, v69
	v_add_f32_e32 v69, 1.0, v75
	v_rcp_f32_e32 v75, v69
	v_pk_mul_f32 v[64:65], v[64:65], v[72:73]
	v_cvt_pk_bf16_f32 v69, v70, v71
	v_cvt_pk_bf16_f32 v70, v64, v65
	v_pk_mul_f32 v[64:65], v[66:67], v[74:75]
	v_lshl_add_u64 v[82:83], v[82:83], 0, v[170:171]
	v_cvt_pk_bf16_f32 v71, v64, v65
	v_lshl_add_u64 v[102:103], v[174:175], 0, s[20:21]
	global_store_dwordx4 v[112:113], v[108:111], off
	global_store_dwordx4 v[82:83], v[76:79], off
	global_store_dwordx4 v[82:83], v[68:71], off offset:256
	v_lshl_add_u64 v[64:65], v[172:173], 0, v[102:103]
	global_load_dwordx4 v[96:99], v[64:65], off nt
	global_load_dwordx4 v[80:83], v[64:65], off offset:256 nt
	v_lshl_add_u64 v[86:87], v[174:175], 0, s[22:23]
	v_lshl_add_u64 v[64:65], v[172:173], 0, v[86:87]
	global_load_dwordx4 v[76:79], v[64:65], off nt
	global_load_dwordx4 v[72:75], v[64:65], off offset:256 nt
	v_lshl_add_u64 v[84:85], v[174:175], 0, s[24:25]
	v_lshl_add_u64 v[100:101], s[8:9], 0, v[100:101]
	v_lshl_add_u64 v[64:65], v[172:173], 0, v[84:85]
	s_waitcnt vmcnt(9)
	v_lshlrev_b32_e32 v104, 16, v88
	v_and_b32_e32 v88, 0xffff0000, v88
	v_mul_f32_e32 v88, 0xbfb8aa3b, v88
	v_exp_f32_e32 v88, v88
	v_mul_f32_e32 v104, 0xbfb8aa3b, v104
	v_exp_f32_e32 v104, v104
	v_lshl_add_u64 v[100:101], v[100:101], 0, v[170:171]
	v_add_f32_e32 v88, 1.0, v88
	v_rcp_f32_e32 v105, v88
	v_lshlrev_b32_e32 v88, 16, v89
	v_and_b32_e32 v89, 0xffff0000, v89
	v_mul_f32_e32 v88, 0xbfb8aa3b, v88
	v_mul_f32_e32 v89, 0xbfb8aa3b, v89
	v_add_f32_e32 v104, 1.0, v104
	v_exp_f32_e32 v88, v88
	v_exp_f32_e32 v89, v89
	v_rcp_f32_e32 v104, v104
	global_load_dwordx4 v[68:71], v[64:65], off nt
	s_nop 0
	global_load_dwordx4 v[64:67], v[64:65], off offset:256 nt
	v_add_f32_e32 v88, 1.0, v88
	v_add_f32_e32 v89, 1.0, v89
	v_pk_mul_f32 v[60:61], v[60:61], v[104:105]
	v_rcp_f32_e32 v88, v88
	v_lshlrev_b32_e32 v104, 16, v90
	v_and_b32_e32 v90, 0xffff0000, v90
	v_rcp_f32_e32 v89, v89
	v_mul_f32_e32 v104, 0xbfb8aa3b, v104
	v_mul_f32_e32 v90, 0xbfb8aa3b, v90
	v_exp_f32_e32 v104, v104
	v_exp_f32_e32 v90, v90
	v_pk_mul_f32 v[62:63], v[62:63], v[88:89]
	v_cvt_pk_bf16_f32 v60, v60, v61
	v_cvt_pk_bf16_f32 v61, v62, v63
	v_lshlrev_b32_e32 v62, 16, v91
	v_add_f32_e32 v104, 1.0, v104
	v_add_f32_e32 v90, 1.0, v90
	v_mul_f32_e32 v62, 0xbfb8aa3b, v62
	v_rcp_f32_e32 v104, v104
	v_rcp_f32_e32 v105, v90
	v_exp_f32_e32 v63, v62
	v_and_b32_e32 v62, 0xffff0000, v91
	v_mul_f32_e32 v62, 0xbfb8aa3b, v62
	v_exp_f32_e32 v88, v62
	v_pk_mul_f32 v[56:57], v[56:57], v[104:105]
	s_nop 0
	v_cvt_pk_bf16_f32 v62, v56, v57
	v_add_f32_e32 v56, 1.0, v63
	s_waitcnt vmcnt(9)
; __device__ __forceinline__ unsigned pk2(float lo, float hi) { const f32x2 v = {lo, hi}; const bf16x2_t b = __builtin_convertvector(v, bf16x2_t); return __builtin_bit_cast(unsigned, b); }
; __device__ __forceinline__ float sigmoid_f(float v) { return __builtin_amdgcn_rcpf(1.f + __expf(-v)); }
;     __device__ __forceinline__ void operator()(const f32x4 (&acc)[2][2][4][2], const pg8::Unit& u, int wr, int wc, int fr, int fq) const {
;     ...
;             for (int m = 0; m < 4; ++m) { bf16_t* rowp = G + (size_t)(row0 + ai * 128 + m * 16) * 2048 + col0;
; #pragma unroll
;                 for (int bj = 0; bj < 2; ++bj) { const u32x4 g = gb[m][bj]; const f32x4 v0 = acc[ai][bj][m][0], v1 = acc[ai][bj][m][1];
;                     u32x4 w; w.x = pk2(sigmoid_f(bflo(g.x)) * v0[0], sigmoid_f(bfhi(g.x)) * v0[1]); w.y = pk2(sigmoid_f(bflo(g.y)) * v0[2], sigmoid_f(bfhi(g.y)) * v0[3]);
;                     w.z = pk2(sigmoid_f(bflo(g.z)) * v1[0], sigmoid_f(bfhi(g.z)) * v1[1]); w.w = pk2(sigmoid_f(bflo(g.w)) * v1[2], sigmoid_f(bfhi(g.w)) * v1[3]);
;                     *(u32x4*)(rowp + bj * 128) = w; } }
	v_lshlrev_b32_e32 v63, 16, v92
	v_add_f32_e32 v57, 1.0, v88
	v_mul_f32_e32 v63, 0xbfb8aa3b, v63
	v_and_b32_e32 v88, 0xffff0000, v92
	v_exp_f32_e32 v63, v63
	v_mul_f32_e32 v88, 0xbfb8aa3b, v88
	v_rcp_f32_e32 v56, v56
	v_exp_f32_e32 v89, v88
	v_rcp_f32_e32 v57, v57
	v_add_f32_e32 v63, 1.0, v63
	v_rcp_f32_e32 v88, v63
	v_add_f32_e32 v63, 1.0, v89
	v_pk_mul_f32 v[56:57], v[58:59], v[56:57]
	v_rcp_f32_e32 v89, v63
	v_cvt_pk_bf16_f32 v63, v56, v57
	v_lshlrev_b32_e32 v56, 16, v93
	v_mul_f32_e32 v56, 0xbfb8aa3b, v56
	v_and_b32_e32 v57, 0xffff0000, v93
	v_exp_f32_e32 v56, v56
	v_mul_f32_e32 v57, 0xbfb8aa3b, v57
	v_exp_f32_e32 v57, v57
	v_pk_mul_f32 v[52:53], v[52:53], v[88:89]
	v_and_b32_e32 v58, 0xffff0000, v94
	v_cvt_pk_bf16_f32 v52, v52, v53
	v_add_f32_e32 v53, 1.0, v56
	v_rcp_f32_e32 v56, v53
	v_add_f32_e32 v53, 1.0, v57
	v_rcp_f32_e32 v57, v53
	v_lshlrev_b32_e32 v53, 16, v94
	v_mul_f32_e32 v53, 0xbfb8aa3b, v53
	v_exp_f32_e32 v53, v53
	v_mul_f32_e32 v58, 0xbfb8aa3b, v58
	v_exp_f32_e32 v58, v58
	v_pk_mul_f32 v[54:55], v[54:55], v[56:57]
	v_lshlrev_b32_e32 v57, 16, v95
	v_add_f32_e32 v53, 1.0, v53
	v_mul_f32_e32 v57, 0xbfb8aa3b, v57
	v_rcp_f32_e32 v56, v53
	v_add_f32_e32 v53, 1.0, v58
	v_exp_f32_e32 v58, v57
	v_and_b32_e32 v57, 0xffff0000, v95
	v_mul_f32_e32 v57, 0xbfb8aa3b, v57
	v_exp_f32_e32 v59, v57
	v_rcp_f32_e32 v57, v53
	v_add_f32_e32 v53, 1.0, v58
	v_rcp_f32_e32 v58, v53
	v_add_f32_e32 v53, 1.0, v59
	v_rcp_f32_e32 v59, v53
	v_pk_mul_f32 v[48:49], v[48:49], v[56:57]
	v_cvt_pk_bf16_f32 v53, v54, v55
	v_cvt_pk_bf16_f32 v54, v48, v49
	v_pk_mul_f32 v[48:49], v[50:51], v[58:59]
	s_waitcnt vmcnt(5)
	v_lshlrev_b32_e32 v50, 16, v96
	v_and_b32_e32 v51, 0xffff0000, v96
	v_mul_f32_e32 v50, 0xbfb8aa3b, v50
	v_mul_f32_e32 v51, 0xbfb8aa3b, v51
	v_exp_f32_e32 v50, v50
	v_exp_f32_e32 v51, v51
	v_cvt_pk_bf16_f32 v55, v48, v49
	global_store_dwordx4 v[100:101], v[52:55], off offset:256
	v_add_f32_e32 v50, 1.0, v50
	v_add_f32_e32 v51, 1.0, v51
	v_lshlrev_b32_e32 v52, 16, v97
	v_and_b32_e32 v53, 0xffff0000, v97
	v_mul_f32_e32 v52, 0xbfb8aa3b, v52
	v_mul_f32_e32 v53, 0xbfb8aa3b, v53
	v_rcp_f32_e32 v50, v50
	v_rcp_f32_e32 v51, v51
	v_exp_f32_e32 v52, v52
	v_exp_f32_e32 v53, v53
	v_lshl_add_u64 v[48:49], s[8:9], 0, v[102:103]
	v_pk_mul_f32 v[44:45], v[44:45], v[50:51]
	v_add_f32_e32 v50, 1.0, v52
	v_add_f32_e32 v51, 1.0, v53
	v_rcp_f32_e32 v50, v50
	v_lshlrev_b32_e32 v52, 16, v98
	v_and_b32_e32 v53, 0xffff0000, v98
	v_rcp_f32_e32 v51, v51
	v_mul_f32_e32 v52, 0xbfb8aa3b, v52
	v_mul_f32_e32 v53, 0xbfb8aa3b, v53
	v_exp_f32_e32 v52, v52
	v_exp_f32_e32 v53, v53
	v_pk_mul_f32 v[46:47], v[46:47], v[50:51]
	v_cvt_pk_bf16_f32 v44, v44, v45
	v_cvt_pk_bf16_f32 v45, v46, v47
	v_lshlrev_b32_e32 v46, 16, v99
	v_add_f32_e32 v52, 1.0, v52
	v_add_f32_e32 v53, 1.0, v53
	v_mul_f32_e32 v46, 0xbfb8aa3b, v46
	v_rcp_f32_e32 v52, v52
	v_rcp_f32_e32 v53, v53
	v_exp_f32_e32 v47, v46
	v_and_b32_e32 v46, 0xffff0000, v99
	v_mul_f32_e32 v46, 0xbfb8aa3b, v46
	v_exp_f32_e32 v50, v46
	v_pk_mul_f32 v[40:41], v[40:41], v[52:53]
	v_lshl_add_u64 v[48:49], v[48:49], 0, v[170:171]
	v_cvt_pk_bf16_f32 v46, v40, v41
	v_add_f32_e32 v40, 1.0, v47
	s_waitcnt vmcnt(5)
	v_lshlrev_b32_e32 v47, 16, v80
	v_add_f32_e32 v41, 1.0, v50
	v_mul_f32_e32 v47, 0xbfb8aa3b, v47
	v_and_b32_e32 v50, 0xffff0000, v80
	v_exp_f32_e32 v47, v47
	v_mul_f32_e32 v50, 0xbfb8aa3b, v50
	v_rcp_f32_e32 v40, v40
	v_exp_f32_e32 v51, v50
	v_rcp_f32_e32 v41, v41
	v_add_f32_e32 v47, 1.0, v47
	v_rcp_f32_e32 v50, v47
	v_add_f32_e32 v47, 1.0, v51
	v_pk_mul_f32 v[40:41], v[42:43], v[40:41]
	v_rcp_f32_e32 v51, v47
	v_cvt_pk_bf16_f32 v47, v40, v41
	v_lshlrev_b32_e32 v40, 16, v81
	v_mul_f32_e32 v40, 0xbfb8aa3b, v40
	v_and_b32_e32 v41, 0xffff0000, v81
	v_exp_f32_e32 v40, v40
	v_mul_f32_e32 v41, 0xbfb8aa3b, v41
	v_exp_f32_e32 v41, v41
	v_pk_mul_f32 v[36:37], v[36:37], v[50:51]
	v_and_b32_e32 v42, 0xffff0000, v82
	v_cvt_pk_bf16_f32 v36, v36, v37
	v_add_f32_e32 v37, 1.0, v40
	v_rcp_f32_e32 v40, v37
	v_add_f32_e32 v37, 1.0, v41
	v_rcp_f32_e32 v41, v37
	v_lshlrev_b32_e32 v37, 16, v82
	v_mul_f32_e32 v37, 0xbfb8aa3b, v37
	v_exp_f32_e32 v37, v37
	v_mul_f32_e32 v42, 0xbfb8aa3b, v42
	v_exp_f32_e32 v42, v42
	v_pk_mul_f32 v[38:39], v[38:39], v[40:41]
	v_lshlrev_b32_e32 v41, 16, v83
	v_add_f32_e32 v37, 1.0, v37
	v_mul_f32_e32 v41, 0xbfb8aa3b, v41
	v_rcp_f32_e32 v40, v37
	v_add_f32_e32 v37, 1.0, v42
	v_exp_f32_e32 v42, v41
	v_and_b32_e32 v41, 0xffff0000, v83
	v_mul_f32_e32 v41, 0xbfb8aa3b, v41
	v_exp_f32_e32 v43, v41
	v_rcp_f32_e32 v41, v37
	v_add_f32_e32 v37, 1.0, v42
	v_rcp_f32_e32 v42, v37
	v_add_f32_e32 v37, 1.0, v43
	v_rcp_f32_e32 v43, v37
	v_pk_mul_f32 v[32:33], v[32:33], v[40:41]
	v_cvt_pk_bf16_f32 v37, v38, v39
	v_cvt_pk_bf16_f32 v38, v32, v33
	v_pk_mul_f32 v[32:33], v[34:35], v[42:43]
	s_waitcnt vmcnt(4)
	v_lshlrev_b32_e32 v34, 16, v76
	v_and_b32_e32 v35, 0xffff0000, v76
	v_mul_f32_e32 v34, 0xbfb8aa3b, v34
	v_mul_f32_e32 v35, 0xbfb8aa3b, v35
	v_exp_f32_e32 v34, v34
	v_exp_f32_e32 v35, v35
	v_cvt_pk_bf16_f32 v39, v32, v33
	global_store_dwordx4 v[48:49], v[36:39], off offset:256
	v_add_f32_e32 v34, 1.0, v34
	v_add_f32_e32 v35, 1.0, v35
	v_lshlrev_b32_e32 v36, 16, v77
	v_and_b32_e32 v37, 0xffff0000, v77
	v_mul_f32_e32 v36, 0xbfb8aa3b, v36
	v_mul_f32_e32 v37, 0xbfb8aa3b, v37
	v_rcp_f32_e32 v34, v34
	v_rcp_f32_e32 v35, v35
	v_exp_f32_e32 v36, v36
	v_exp_f32_e32 v37, v37
	v_lshl_add_u64 v[32:33], s[8:9], 0, v[86:87]
	v_pk_mul_f32 v[28:29], v[28:29], v[34:35]
	v_add_f32_e32 v34, 1.0, v36
	v_add_f32_e32 v35, 1.0, v37
	v_rcp_f32_e32 v34, v34
	v_lshlrev_b32_e32 v36, 16, v78
	v_and_b32_e32 v37, 0xffff0000, v78
	v_rcp_f32_e32 v35, v35
	v_mul_f32_e32 v36, 0xbfb8aa3b, v36
	v_mul_f32_e32 v37, 0xbfb8aa3b, v37
	v_exp_f32_e32 v36, v36
	v_exp_f32_e32 v37, v37
	v_pk_mul_f32 v[30:31], v[30:31], v[34:35]
	v_cvt_pk_bf16_f32 v28, v28, v29
	v_cvt_pk_bf16_f32 v29, v30, v31
	v_lshlrev_b32_e32 v30, 16, v79
	v_add_f32_e32 v36, 1.0, v36
	v_add_f32_e32 v37, 1.0, v37
	v_mul_f32_e32 v30, 0xbfb8aa3b, v30
	v_rcp_f32_e32 v36, v36
	v_rcp_f32_e32 v37, v37
	v_exp_f32_e32 v31, v30
	v_and_b32_e32 v30, 0xffff0000, v79
	v_mul_f32_e32 v30, 0xbfb8aa3b, v30
	v_exp_f32_e32 v34, v30
	v_pk_mul_f32 v[24:25], v[24:25], v[36:37]
	v_lshl_add_u64 v[32:33], v[32:33], 0, v[170:171]
	v_cvt_pk_bf16_f32 v30, v24, v25
	v_add_f32_e32 v24, 1.0, v31
	s_waitcnt vmcnt(4)
; #define PG8_BAR __builtin_amdgcn_s_barrier()
; __device__ __forceinline__ unsigned pk2(float lo, float hi) { const f32x2 v = {lo, hi}; const bf16x2_t b = __builtin_convertvector(v, bf16x2_t); return __builtin_bit_cast(unsigned, b); }
; __device__ __forceinline__ float sigmoid_f(float v) { return __builtin_amdgcn_rcpf(1.f + __expf(-v)); }
; template <class Epi, class Sched, bool ALIGN_EPI = false, bool SP2 = false>
; __device__ __forceinline__ void gemm_phase(PG8_LAS unsigned char* lds, const Gemm g, const Sched& S, const Epi& E) {
;     ...
;         if constexpr (ALIGN_EPI) { if (wr == 0) PG8_BAR; }
;         if constexpr (!Epi::AFTER_DRAIN) { E(acc, cur, wr, wc, fr, fq); S.done(cur); }
;         if (!has_next) break;
; #pragma unroll
;         for (int a = 0; a < 2; ++a)
; #pragma unroll
;             for (int b = 0; b < 2; ++b)
; #pragma unroll
;                 for (int m = 0; m < 4; ++m)
; #pragma unroll
;                     for (int n = 0; n < 2; ++n) acc[a][b][m][n] = (f32x4){0.f, 0.f, 0.f, 0.f};
;         cur = nxt; cA = nA; cB = nB; ++ui;
;         if constexpr (ALIGN_EPI) { if (wr == 1) PG8_BAR; }
;     __device__ __forceinline__ void operator()(const f32x4 (&acc)[2][2][4][2], const pg8::Unit& u, int wr, int wc, int fr, int fq) const {
;     ...
;             for (int m = 0; m < 4; ++m) { bf16_t* rowp = G + (size_t)(row0 + ai * 128 + m * 16) * 2048 + col0;
; #pragma unroll
;                 for (int bj = 0; bj < 2; ++bj) { const u32x4 g = gb[m][bj]; const f32x4 v0 = acc[ai][bj][m][0], v1 = acc[ai][bj][m][1];
;                     u32x4 w; w.x = pk2(sigmoid_f(bflo(g.x)) * v0[0], sigmoid_f(bfhi(g.x)) * v0[1]); w.y = pk2(sigmoid_f(bflo(g.y)) * v0[2], sigmoid_f(bfhi(g.y)) * v0[3]);
;                     w.z = pk2(sigmoid_f(bflo(g.z)) * v1[0], sigmoid_f(bfhi(g.z)) * v1[1]); w.w = pk2(sigmoid_f(bflo(g.w)) * v1[2], sigmoid_f(bfhi(g.w)) * v1[3]);
;                     *(u32x4*)(rowp + bj * 128) = w; } }
	v_lshlrev_b32_e32 v31, 16, v72
	v_add_f32_e32 v25, 1.0, v34
	v_mul_f32_e32 v31, 0xbfb8aa3b, v31
	v_and_b32_e32 v34, 0xffff0000, v72
	v_exp_f32_e32 v31, v31
	v_mul_f32_e32 v34, 0xbfb8aa3b, v34
	v_rcp_f32_e32 v24, v24
	v_exp_f32_e32 v35, v34
	v_rcp_f32_e32 v25, v25
	v_add_f32_e32 v31, 1.0, v31
	v_rcp_f32_e32 v34, v31
	v_add_f32_e32 v31, 1.0, v35
	v_pk_mul_f32 v[24:25], v[26:27], v[24:25]
	v_rcp_f32_e32 v35, v31
	v_cvt_pk_bf16_f32 v31, v24, v25
	v_lshlrev_b32_e32 v24, 16, v73
	v_mul_f32_e32 v24, 0xbfb8aa3b, v24
	v_and_b32_e32 v25, 0xffff0000, v73
	v_exp_f32_e32 v24, v24
	v_mul_f32_e32 v25, 0xbfb8aa3b, v25
	v_exp_f32_e32 v25, v25
	v_pk_mul_f32 v[20:21], v[20:21], v[34:35]
	v_and_b32_e32 v26, 0xffff0000, v74
	v_cvt_pk_bf16_f32 v20, v20, v21
	v_add_f32_e32 v21, 1.0, v24
	v_rcp_f32_e32 v24, v21
	v_add_f32_e32 v21, 1.0, v25
	v_rcp_f32_e32 v25, v21
	v_lshlrev_b32_e32 v21, 16, v74
	v_mul_f32_e32 v21, 0xbfb8aa3b, v21
	v_exp_f32_e32 v21, v21
	v_mul_f32_e32 v26, 0xbfb8aa3b, v26
	v_exp_f32_e32 v26, v26
	v_pk_mul_f32 v[22:23], v[22:23], v[24:25]
	v_lshlrev_b32_e32 v25, 16, v75
	v_add_f32_e32 v21, 1.0, v21
	v_mul_f32_e32 v25, 0xbfb8aa3b, v25
	v_rcp_f32_e32 v24, v21
	v_add_f32_e32 v21, 1.0, v26
	v_exp_f32_e32 v26, v25
	v_and_b32_e32 v25, 0xffff0000, v75
	v_mul_f32_e32 v25, 0xbfb8aa3b, v25
	v_exp_f32_e32 v27, v25
	v_rcp_f32_e32 v25, v21
	v_add_f32_e32 v21, 1.0, v26
	v_rcp_f32_e32 v26, v21
	v_add_f32_e32 v21, 1.0, v27
	v_rcp_f32_e32 v27, v21
	v_pk_mul_f32 v[16:17], v[16:17], v[24:25]
	v_cvt_pk_bf16_f32 v21, v22, v23
	v_cvt_pk_bf16_f32 v22, v16, v17
	v_pk_mul_f32 v[16:17], v[18:19], v[26:27]
	s_waitcnt vmcnt(3)
	v_lshlrev_b32_e32 v18, 16, v68
	v_and_b32_e32 v19, 0xffff0000, v68
	v_mul_f32_e32 v18, 0xbfb8aa3b, v18
	v_mul_f32_e32 v19, 0xbfb8aa3b, v19
	v_exp_f32_e32 v18, v18
	v_exp_f32_e32 v19, v19
	v_cvt_pk_bf16_f32 v23, v16, v17
	global_store_dwordx4 v[32:33], v[20:23], off offset:256
	v_add_f32_e32 v18, 1.0, v18
	v_add_f32_e32 v19, 1.0, v19
	v_lshlrev_b32_e32 v20, 16, v69
	v_and_b32_e32 v21, 0xffff0000, v69
	v_mul_f32_e32 v20, 0xbfb8aa3b, v20
	v_mul_f32_e32 v21, 0xbfb8aa3b, v21
	v_rcp_f32_e32 v18, v18
	v_rcp_f32_e32 v19, v19
	v_exp_f32_e32 v20, v20
	v_exp_f32_e32 v21, v21
	v_lshl_add_u64 v[16:17], s[8:9], 0, v[84:85]
	v_pk_mul_f32 v[12:13], v[12:13], v[18:19]
	v_add_f32_e32 v18, 1.0, v20
	v_add_f32_e32 v19, 1.0, v21
	v_rcp_f32_e32 v18, v18
	v_lshlrev_b32_e32 v20, 16, v70
	v_and_b32_e32 v21, 0xffff0000, v70
	v_rcp_f32_e32 v19, v19
	v_mul_f32_e32 v20, 0xbfb8aa3b, v20
	v_mul_f32_e32 v21, 0xbfb8aa3b, v21
	v_exp_f32_e32 v20, v20
	v_exp_f32_e32 v21, v21
	v_pk_mul_f32 v[14:15], v[14:15], v[18:19]
	v_cvt_pk_bf16_f32 v12, v12, v13
	v_cvt_pk_bf16_f32 v13, v14, v15
	v_lshlrev_b32_e32 v14, 16, v71
	v_add_f32_e32 v20, 1.0, v20
	v_add_f32_e32 v21, 1.0, v21
	v_mul_f32_e32 v14, 0xbfb8aa3b, v14
	v_rcp_f32_e32 v20, v20
	v_rcp_f32_e32 v21, v21
	v_exp_f32_e32 v15, v14
	v_and_b32_e32 v14, 0xffff0000, v71
	v_mul_f32_e32 v14, 0xbfb8aa3b, v14
	v_exp_f32_e32 v18, v14
	v_pk_mul_f32 v[8:9], v[8:9], v[20:21]
	v_lshl_add_u64 v[16:17], v[16:17], 0, v[170:171]
	v_cvt_pk_bf16_f32 v14, v8, v9
	v_add_f32_e32 v8, 1.0, v15
	s_waitcnt vmcnt(3)
	v_lshlrev_b32_e32 v15, 16, v64
	v_add_f32_e32 v9, 1.0, v18
	v_mul_f32_e32 v15, 0xbfb8aa3b, v15
	v_and_b32_e32 v18, 0xffff0000, v64
	v_exp_f32_e32 v15, v15
	v_mul_f32_e32 v18, 0xbfb8aa3b, v18
	v_rcp_f32_e32 v8, v8
	v_exp_f32_e32 v19, v18
	v_rcp_f32_e32 v9, v9
	v_add_f32_e32 v15, 1.0, v15
	v_rcp_f32_e32 v18, v15
	v_add_f32_e32 v15, 1.0, v19
	v_pk_mul_f32 v[8:9], v[10:11], v[8:9]
	v_rcp_f32_e32 v19, v15
	v_cvt_pk_bf16_f32 v15, v8, v9
	v_lshlrev_b32_e32 v8, 16, v65
	v_mul_f32_e32 v8, 0xbfb8aa3b, v8
	v_and_b32_e32 v9, 0xffff0000, v65
	v_exp_f32_e32 v8, v8
	v_mul_f32_e32 v9, 0xbfb8aa3b, v9
	v_exp_f32_e32 v9, v9
	v_pk_mul_f32 v[4:5], v[4:5], v[18:19]
	v_and_b32_e32 v10, 0xffff0000, v66
	v_cvt_pk_bf16_f32 v4, v4, v5
	v_add_f32_e32 v5, 1.0, v8
	v_rcp_f32_e32 v8, v5
	v_add_f32_e32 v5, 1.0, v9
	v_rcp_f32_e32 v9, v5
	v_lshlrev_b32_e32 v5, 16, v66
	v_mul_f32_e32 v5, 0xbfb8aa3b, v5
	v_exp_f32_e32 v5, v5
	v_mul_f32_e32 v10, 0xbfb8aa3b, v10
	v_exp_f32_e32 v10, v10
	v_pk_mul_f32 v[6:7], v[6:7], v[8:9]
	v_lshlrev_b32_e32 v9, 16, v67
	v_add_f32_e32 v5, 1.0, v5
	v_mul_f32_e32 v9, 0xbfb8aa3b, v9
	v_rcp_f32_e32 v8, v5
	v_add_f32_e32 v5, 1.0, v10
	v_exp_f32_e32 v10, v9
	v_and_b32_e32 v9, 0xffff0000, v67
	v_mul_f32_e32 v9, 0xbfb8aa3b, v9
	v_exp_f32_e32 v11, v9
	v_rcp_f32_e32 v9, v5
	v_add_f32_e32 v5, 1.0, v10
	v_rcp_f32_e32 v10, v5
	v_add_f32_e32 v5, 1.0, v11
	v_rcp_f32_e32 v11, v5
	v_pk_mul_f32 v[0:1], v[0:1], v[8:9]
	v_cvt_pk_bf16_f32 v5, v6, v7
	v_cvt_pk_bf16_f32 v6, v0, v1
	v_pk_mul_f32 v[0:1], v[2:3], v[10:11]
	global_store_dwordx4 v[100:101], v[60:63], off
	v_cvt_pk_bf16_f32 v7, v0, v1
	global_store_dwordx4 v[48:49], v[44:47], off
	global_store_dwordx4 v[32:33], v[28:31], off
	global_store_dwordx4 v[16:17], v[12:15], off
	global_store_dwordx4 v[16:17], v[4:7], off offset:256
	s_cbranch_vccnz .LBB0_832
	s_andn2_b64 vcc, exec, s[12:13]
	s_cbranch_vccnz .LBB0_831
	s_barrier
	s_branch .LBB0_831

; __global__ void __launch_bounds__(512, 2) mk_fwd(Args a) {
;     extern __shared__ __attribute__((aligned(16))) unsigned char smem[];
;     const int tid = threadIdx.x, lane = tid & 63, wave = __builtin_amdgcn_readfirstlane(tid >> 6);
	.amdhsa_kernel _Z6mk_fwd4Args
		.amdhsa_group_segment_fixed_size 0
		.amdhsa_private_segment_fixed_size 0
		.amdhsa_kernarg_size 408
		.amdhsa_user_sgpr_count 2
		.amdhsa_user_sgpr_dispatch_ptr 0
		.amdhsa_user_sgpr_queue_ptr 0
		.amdhsa_user_sgpr_kernarg_segment_ptr 1
		.amdhsa_user_sgpr_dispatch_id 0
		.amdhsa_user_sgpr_kernarg_preload_length 0
		.amdhsa_user_sgpr_kernarg_preload_offset 0
		.amdhsa_user_sgpr_private_segment_size 0
		.amdhsa_uses_dynamic_stack 0
		.amdhsa_enable_private_segment 0
		.amdhsa_system_sgpr_workgroup_id_x 1
		.amdhsa_system_sgpr_workgroup_id_y 0
		.amdhsa_system_sgpr_workgroup_id_z 0
		.amdhsa_system_sgpr_workgroup_info 0
		.amdhsa_system_vgpr_workitem_id 2
		.amdhsa_next_free_vgpr 256
		.amdhsa_next_free_sgpr 98
		.amdhsa_accum_offset 256
		.amdhsa_reserve_vcc 1
		.amdhsa_float_round_mode_32 0
		.amdhsa_float_round_mode_16_64 0
		.amdhsa_float_denorm_mode_32 3
		.amdhsa_float_denorm_mode_16_64 3
		.amdhsa_dx10_clamp 1
		.amdhsa_ieee_mode 1
		.amdhsa_fp16_overflow 0
		.amdhsa_tg_split 0
		.amdhsa_exception_fp_ieee_invalid_op 0
		.amdhsa_exception_fp_denorm_src 0
		.amdhsa_exception_fp_ieee_div_zero 0
		.amdhsa_exception_fp_ieee_overflow 0
		.amdhsa_exception_fp_ieee_underflow 0
		.amdhsa_exception_fp_ieee_inexact 0
		.amdhsa_exception_int_div_zero 0
	.end_amdhsa_kernel

amdhsa.kernels:
  - .agpr_count:     0
    .args:
      - .offset:         0
        .size:           152
        .value_kind:     by_value
      - .offset:         152
        .size:           4
        .value_kind:     hidden_block_count_x
      - .offset:         156
        .size:           4
        .value_kind:     hidden_block_count_y
      - .offset:         160
        .size:           4
        .value_kind:     hidden_block_count_z
      - .offset:         164
        .size:           2
        .value_kind:     hidden_group_size_x
      - .offset:         166
        .size:           2
        .value_kind:     hidden_group_size_y
      - .offset:         168
        .size:           2
        .value_kind:     hidden_group_size_z
      - .offset:         170
        .size:           2
        .value_kind:     hidden_remainder_x
      - .offset:         172
        .size:           2
        .value_kind:     hidden_remainder_y
      - .offset:         174
        .size:           2
        .value_kind:     hidden_remainder_z
      - .offset:         192
        .size:           8
        .value_kind:     hidden_global_offset_x
      - .offset:         200
        .size:           8
        .value_kind:     hidden_global_offset_y
      - .offset:         208
        .size:           8
        .value_kind:     hidden_global_offset_z
      - .offset:         216
        .size:           2
        .value_kind:     hidden_grid_dims
      - .offset:         240
        .size:           8
        .value_kind:     hidden_multigrid_sync_arg
      - .offset:         272
        .size:           4
        .value_kind:     hidden_dynamic_lds_size
    .group_segment_fixed_size: 0
    .kernarg_segment_align: 8
    .kernarg_segment_size: 408
    .language:       OpenCL C
    .language_version:
      - 2
      - 0
    .max_flat_workgroup_size: 512
    .name:           _Z6mk_fwd4Args
    .private_segment_fixed_size: 0
    .sgpr_count:     104
    .sgpr_spill_count: 10
    .symbol:         _Z6mk_fwd4Args.kd
    .uniform_work_group_size: 1
    .uses_dynamic_stack: false
    .vgpr_count:     256
    .vgpr_spill_count: 0
    .wavefront_size: 64
